# V4 minus the static s_setprio 1 for waves 4-7 in the attention phase (A/B of the priority raise)
# speedup vs baseline: 1.0037x; 1.0037x over previous
; #define OPAQUE_TID() int tid = MYTID(); asm volatile("" : "+v"(tid)); const int lane = tid & 63, wave = __builtin_amdgcn_readfirstlane(tid >> 6); (void)lane; (void)wave
; __global__ void __launch_bounds__(NTHREADS, 2) fwd_kernel(Args a) {
;     ...
;     if (IN(4)) { OPAQUE_TID();
;         if (wave >= 4) __builtin_amdgcn_s_setprio(1);
;         for (int U = vcu; U < 256; U += G) { int tu = tid; asm volatile("" : "+v"(tu)); compress_unit(U, a, lds, tu, wave, tu & 63); }
.LBB0_742:
	s_cmp_lt_i32 s42, 5
	s_cselect_b64 s[0:1], -1, 0
	s_and_b64 s[0:1], s[0:1], s[2:3]
	v_writelane_b32 v248, s0, 3
	s_andn2_b64 vcc, exec, s[0:1]
	s_nop 0
	v_writelane_b32 v248, s1, 4
	s_cbranch_vccnz .LBB0_990
	v_mbcnt_hi_u32_b32 v0, -1, v230
	v_readlane_b32 s0, v248, 0
	s_nop 1
	v_add_u32_e32 v214, s0, v0
	v_mov_b32_e32 v215, v214
	s_nop 0
	v_readfirstlane_b32 s1, v215
	s_ashr_i32 s0, s1, 6
	s_cmp_lt_i32 s0, 4
	s_cbranch_scc1 .LBB0_745
	s_nop 0
